# lin_C2 (both variants): A-operand LDS reads of the Q.C^T MFMA section fetched 7 ahead into a rotating pool of unused register quads
# baseline (speedup 1.0000x reference)
.LBB0_76:
	v_lshl_add_u64 v[4:5], v[56:57], 0, s[16:17]
	v_mad_u64_u32 v[8:9], s[18:19], v4, s72, v[58:59]
	v_mov_b32_e32 v2, v9
	v_mad_u64_u32 v[10:11], s[18:19], v5, s72, v[2:3]
	v_mov_b32_e32 v9, v10
	v_add_co_u32_e32 v114, vcc, s20, v8
	s_nop 1
	v_addc_co_u32_e32 v115, vcc, 0, v10, vcc
	v_add_co_u32_e32 v116, vcc, s24, v8
	s_nop 1
	v_addc_co_u32_e32 v117, vcc, 0, v10, vcc
	v_add_co_u32_e32 v118, vcc, s25, v8
	s_nop 1
	v_addc_co_u32_e32 v119, vcc, 0, v10, vcc
	global_load_dwordx4 v[120:123], v[8:9], off
	global_load_dwordx4 v[124:127], v[114:115], off
	global_load_dwordx4 v[128:131], v[116:117], off
	global_load_dwordx4 v[132:135], v[118:119], off
	v_lshl_add_u64 v[98:99], v[60:61], 0, s[16:17]
	v_mad_u64_u32 v[70:71], s[16:17], v98, s72, v[66:67]
	v_mov_b32_e32 v2, v71
	v_lshlrev_b64 v[84:85], 11, v[98:99]
	v_add_u32_e32 v110, v43, v42
	v_mad_u64_u32 v[6:7], s[16:17], v99, s72, v[2:3]
	v_lshlrev_b64 v[98:99], 4, v[98:99]
	v_lshl_or_b32 v98, s13, 2, v98
	v_lshl_add_u64 v[4:5], v[62:63], 0, v[84:85]
	v_mov_b32_e32 v71, v6
	v_lshl_add_u64 v[100:101], s[6:7], 0, v[98:99]
	v_lshl_add_u64 v[98:99], s[0:1], 0, v[98:99]
	global_load_dwordx4 v[32:35], v[4:5], off
	global_load_dwordx2 v[86:87], v[70:71], off offset:3072
	global_load_dwordx4 v[28:31], v[4:5], off offset:64
	global_load_dwordx2 v[82:83], v[70:71], off offset:3104
	global_load_dwordx4 v[24:27], v[4:5], off offset:128
	global_load_dwordx2 v[80:81], v[70:71], off offset:3136
	global_load_dwordx4 v[20:23], v[4:5], off offset:192
	global_load_dwordx2 v[78:79], v[70:71], off offset:3168
	global_load_dwordx4 v[16:19], v[4:5], off offset:256
	global_load_dwordx2 v[76:77], v[70:71], off offset:3200
	global_load_dwordx4 v[12:15], v[4:5], off offset:320
	global_load_dwordx2 v[74:75], v[70:71], off offset:3232
	global_load_dwordx4 v[8:11], v[4:5], off offset:384
	global_load_dwordx2 v[72:73], v[70:71], off offset:3264
	s_nop 0
	global_load_dwordx4 v[4:7], v[4:5], off offset:448
	s_nop 0
	global_load_dwordx2 v[70:71], v[70:71], off offset:3296
	s_nop 0
	global_load_dword v2, v[100:101], off
	global_load_dword v97, v[98:99], off
	s_waitcnt lgkmcnt(0)
	s_barrier
	s_waitcnt vmcnt(21)
	ds_write_b128 v96, v[120:123] offset:34816
	s_waitcnt vmcnt(20)
	ds_write_b128 v96, v[124:127] offset:43520
	s_waitcnt vmcnt(19)
	ds_write_b128 v96, v[128:131] offset:52224
	s_waitcnt vmcnt(18)
	ds_write_b128 v96, v[132:135] offset:60928
	s_waitcnt lgkmcnt(0)
	s_barrier
	ds_read_b128 v[98:101], v110 offset:34816
	ds_read_b128 v[102:105], v110 offset:34880
	ds_read_b128 v[106:109], v110 offset:34944
	ds_read_b128 v[110:113], v110 offset:35008
	ds_read_b128 v[146:149], v93
	ds_read_b128 v[150:153], v93 offset:64
	ds_read_b128 v[154:157], v93 offset:128
	ds_read_b128 v[158:161], v93 offset:192
	ds_read_b128 v[168:171], v93 offset:4352
	ds_read_b128 v[238:241], v93 offset:4416
	ds_read_b128 v[242:245], v93 offset:4480
	s_waitcnt lgkmcnt(6)
	v_mfma_f32_16x16x32_bf16 v[114:117], v[146:149], v[98:101], 0
	ds_read_b128 v[246:249], v93 offset:4544
	s_waitcnt lgkmcnt(6)
	v_mfma_f32_16x16x32_bf16 v[114:117], v[150:153], v[102:105], v[114:117]
	ds_read_b128 v[146:149], v93 offset:8704
	s_waitcnt lgkmcnt(6)
	v_mfma_f32_16x16x32_bf16 v[114:117], v[154:157], v[106:109], v[114:117]
	ds_read_b128 v[150:153], v93 offset:8768
	s_waitcnt lgkmcnt(6)
	v_mfma_f32_16x16x32_bf16 v[114:117], v[158:161], v[110:113], v[114:117]
	ds_read_b128 v[154:157], v93 offset:8832
	s_waitcnt lgkmcnt(6)
	v_mfma_f32_16x16x32_bf16 v[118:121], v[168:171], v[98:101], 0
	ds_read_b128 v[158:161], v93 offset:8896
	s_waitcnt lgkmcnt(6)
	v_mfma_f32_16x16x32_bf16 v[118:121], v[238:241], v[102:105], v[118:121]
	ds_read_b128 v[168:171], v93 offset:13056
	s_waitcnt lgkmcnt(6)
	v_mfma_f32_16x16x32_bf16 v[118:121], v[242:245], v[106:109], v[118:121]
	ds_read_b128 v[238:241], v93 offset:13120
	s_waitcnt lgkmcnt(6)
	v_mfma_f32_16x16x32_bf16 v[118:121], v[246:249], v[110:113], v[118:121]
	ds_read_b128 v[242:245], v93 offset:13184
	s_waitcnt lgkmcnt(6)
	v_mfma_f32_16x16x32_bf16 v[122:125], v[146:149], v[98:101], 0
	ds_read_b128 v[246:249], v93 offset:13248
	s_waitcnt lgkmcnt(6)
	v_mfma_f32_16x16x32_bf16 v[122:125], v[150:153], v[102:105], v[122:125]
	ds_read_b128 v[146:149], v93 offset:17408
	s_waitcnt lgkmcnt(6)
	v_mfma_f32_16x16x32_bf16 v[122:125], v[154:157], v[106:109], v[122:125]
	ds_read_b128 v[150:153], v93 offset:17472
	s_waitcnt lgkmcnt(6)
	v_mfma_f32_16x16x32_bf16 v[122:125], v[158:161], v[110:113], v[122:125]
	ds_read_b128 v[154:157], v93 offset:17536
	s_waitcnt lgkmcnt(6)
	v_mfma_f32_16x16x32_bf16 v[126:129], v[168:171], v[98:101], 0
	ds_read_b128 v[158:161], v93 offset:17600
	s_waitcnt lgkmcnt(6)
	v_mfma_f32_16x16x32_bf16 v[126:129], v[238:241], v[102:105], v[126:129]
	ds_read_b128 v[168:171], v93 offset:21760
	s_waitcnt lgkmcnt(6)
	v_mfma_f32_16x16x32_bf16 v[126:129], v[242:245], v[106:109], v[126:129]
	ds_read_b128 v[238:241], v93 offset:21824
	s_waitcnt lgkmcnt(6)
	v_mfma_f32_16x16x32_bf16 v[126:129], v[246:249], v[110:113], v[126:129]
	ds_read_b128 v[242:245], v93 offset:21888
	s_waitcnt lgkmcnt(6)
	v_mfma_f32_16x16x32_bf16 v[130:133], v[146:149], v[98:101], 0
	ds_read_b128 v[246:249], v93 offset:21952
	s_waitcnt lgkmcnt(6)
	v_mfma_f32_16x16x32_bf16 v[130:133], v[150:153], v[102:105], v[130:133]
	ds_read_b128 v[146:149], v93 offset:26112
	s_waitcnt lgkmcnt(6)
	v_mfma_f32_16x16x32_bf16 v[130:133], v[154:157], v[106:109], v[130:133]
	ds_read_b128 v[150:153], v93 offset:26176
	s_waitcnt lgkmcnt(6)
	v_mfma_f32_16x16x32_bf16 v[130:133], v[158:161], v[110:113], v[130:133]
	ds_read_b128 v[154:157], v93 offset:26240
	s_waitcnt lgkmcnt(6)
	v_mfma_f32_16x16x32_bf16 v[134:137], v[168:171], v[98:101], 0
	ds_read_b128 v[158:161], v93 offset:26304
	s_waitcnt lgkmcnt(6)
	v_mfma_f32_16x16x32_bf16 v[134:137], v[238:241], v[102:105], v[134:137]
	ds_read_b128 v[168:171], v93 offset:30464
	s_waitcnt lgkmcnt(6)
	v_mfma_f32_16x16x32_bf16 v[134:137], v[242:245], v[106:109], v[134:137]
	ds_read_b128 v[238:241], v93 offset:30528
	s_waitcnt lgkmcnt(6)
	v_mfma_f32_16x16x32_bf16 v[134:137], v[246:249], v[110:113], v[134:137]
	ds_read_b128 v[242:245], v93 offset:30592
	s_waitcnt lgkmcnt(6)
	v_mfma_f32_16x16x32_bf16 v[138:141], v[146:149], v[98:101], 0
	ds_read_b128 v[246:249], v93 offset:30656
	s_waitcnt lgkmcnt(6)
	v_mfma_f32_16x16x32_bf16 v[138:141], v[150:153], v[102:105], v[138:141]
	s_waitcnt lgkmcnt(5)
	v_mfma_f32_16x16x32_bf16 v[138:141], v[154:157], v[106:109], v[138:141]
	s_waitcnt lgkmcnt(4)
	v_mfma_f32_16x16x32_bf16 v[138:141], v[158:161], v[110:113], v[138:141]
	s_waitcnt lgkmcnt(3)
	v_mfma_f32_16x16x32_bf16 v[98:101], v[168:171], v[98:101], 0
	s_waitcnt lgkmcnt(2)
	v_mfma_f32_16x16x32_bf16 v[98:101], v[238:241], v[102:105], v[98:101]
	s_waitcnt lgkmcnt(1)
	v_mfma_f32_16x16x32_bf16 v[98:101], v[242:245], v[106:109], v[98:101]
	s_waitcnt lgkmcnt(0)
	v_mfma_f32_16x16x32_bf16 v[98:101], v[246:249], v[110:113], v[98:101]
	s_waitcnt vmcnt(1)
	v_mul_f32_e32 v2, 0x3db504f3, v2
	s_nop 4
	v_fma_f32 v32, v2, v114, v32
	v_fma_f32 v33, v2, v115, v33
	v_pk_fma_f32 v[34:35], v[2:3], v[116:117], v[34:35] op_sel_hi:[0,1,1]
	v_pk_fma_f32 v[24:25], v[2:3], v[122:123], v[24:25] op_sel_hi:[0,1,1]
	v_pk_fma_f32 v[12:13], v[2:3], v[134:135], v[12:13] op_sel_hi:[0,1,1]
	ds_read_b128 v[102:105], v94 offset:34816
	ds_read_b128 v[106:109], v94 offset:34832
	ds_read_b128 v[110:113], v94 offset:34848
	ds_read_b128 v[142:145], v94 offset:34864
	ds_read_b128 v[146:149], v95
	ds_read_b128 v[150:153], v95 offset:16
	ds_read_b128 v[154:157], v95 offset:32
	ds_read_b128 v[158:161], v95 offset:48
	s_waitcnt lgkmcnt(7)
	v_and_b32_e32 v166, 0xffff0000, v102
	s_waitcnt lgkmcnt(6)
	v_and_b32_e32 v167, 0xffff0000, v106
	v_lshlrev_b32_e32 v163, 16, v106
	s_waitcnt lgkmcnt(1)
	v_mov_b32_e32 v165, v154
	v_mov_b32_e32 v154, v147
	v_lshlrev_b32_e32 v162, 16, v102
	v_mov_b32_e32 v164, v146
	v_pk_mul_f32 v[146:147], v[154:155], v[166:167]
	v_lshlrev_b32_e32 v155, 16, v107
	v_pk_fma_f32 v[146:147], v[164:165], v[162:163], v[146:147]
	v_lshlrev_b32_e32 v154, 16, v103
	v_mov_b32_e32 v162, v148
	v_mov_b32_e32 v163, v156
	v_pk_fma_f32 v[146:147], v[162:163], v[154:155], v[146:147]
	v_and_b32_e32 v107, 0xffff0000, v107
	v_and_b32_e32 v106, 0xffff0000, v103
	v_mov_b32_e32 v156, v149
	v_pk_fma_f32 v[102:103], v[156:157], v[106:107], v[146:147]
	v_lshlrev_b32_e32 v107, 16, v108
	v_lshlrev_b32_e32 v106, 16, v104
	v_mov_b32_e32 v146, v150
	s_waitcnt lgkmcnt(0)
	v_mov_b32_e32 v147, v158
	v_pk_fma_f32 v[102:103], v[146:147], v[106:107], v[102:103]
	v_and_b32_e32 v107, 0xffff0000, v108
	v_and_b32_e32 v106, 0xffff0000, v104
	v_mov_b32_e32 v158, v151
	v_pk_fma_f32 v[102:103], v[158:159], v[106:107], v[102:103]
	v_lshlrev_b32_e32 v107, 16, v109
	v_lshlrev_b32_e32 v106, 16, v105
	v_mov_b32_e32 v146, v152
	v_mov_b32_e32 v147, v160
	v_pk_fma_f32 v[102:103], v[146:147], v[106:107], v[102:103]
	v_and_b32_e32 v107, 0xffff0000, v109
	v_and_b32_e32 v106, 0xffff0000, v105
	v_mov_b32_e32 v160, v153
	v_pk_fma_f32 v[102:103], v[160:161], v[106:107], v[102:103]
	v_and_b32_e32 v159, 0xffff0000, v142
	v_add_f32_e32 v102, 0, v102
	v_add_f32_e32 v160, v102, v103
	ds_read_b128 v[102:105], v95 offset:80
	ds_read_b128 v[106:109], v95 offset:112
	ds_read_b128 v[146:149], v95 offset:64
	ds_read_b128 v[150:153], v95 offset:96
	v_and_b32_e32 v158, 0xffff0000, v110
	v_lshlrev_b32_e32 v155, 16, v142
	v_lshlrev_b32_e32 v154, 16, v110
	s_waitcnt lgkmcnt(1)
	v_mov_b32_e32 v156, v146
	s_waitcnt lgkmcnt(0)
	v_mov_b32_e32 v157, v150
	v_mov_b32_e32 v150, v147
	v_pk_mul_f32 v[146:147], v[150:151], v[158:159]
	v_lshlrev_b32_e32 v151, 16, v143
	v_pk_fma_f32 v[146:147], v[156:157], v[154:155], v[146:147]
	v_lshlrev_b32_e32 v150, 16, v111
	v_mov_b32_e32 v154, v148
	v_mov_b32_e32 v155, v152
	v_pk_fma_f32 v[146:147], v[154:155], v[150:151], v[146:147]
	v_and_b32_e32 v143, 0xffff0000, v143
	v_and_b32_e32 v142, 0xffff0000, v111
	v_mov_b32_e32 v152, v149
	v_pk_fma_f32 v[110:111], v[152:153], v[142:143], v[146:147]
	v_lshlrev_b32_e32 v143, 16, v144
	v_lshlrev_b32_e32 v142, 16, v112
	v_mov_b32_e32 v146, v102
	v_mov_b32_e32 v147, v106
	v_pk_fma_f32 v[110:111], v[146:147], v[142:143], v[110:111]
	v_and_b32_e32 v143, 0xffff0000, v144
	v_and_b32_e32 v142, 0xffff0000, v112
	v_mov_b32_e32 v106, v103
	v_pk_fma_f32 v[102:103], v[106:107], v[142:143], v[110:111]
	v_lshlrev_b32_e32 v107, 16, v145
	v_lshlrev_b32_e32 v106, 16, v113
	v_mov_b32_e32 v110, v104
	v_mov_b32_e32 v111, v108
	v_pk_fma_f32 v[102:103], v[110:111], v[106:107], v[102:103]
	v_and_b32_e32 v107, 0xffff0000, v145
	v_and_b32_e32 v106, 0xffff0000, v113
	v_mov_b32_e32 v108, v105
	v_pk_fma_f32 v[102:103], v[108:109], v[106:107], v[102:103]
	v_pk_fma_f32 v[112:113], v[2:3], v[130:131], v[16:17] op_sel_hi:[0,1,1]
	v_add_f32_e32 v102, v160, v102
	v_add_f32_e32 v102, v102, v103
	ds_bpermute_b32 v103, v91, v102
	v_pk_fma_f32 v[16:17], v[2:3], v[132:133], v[18:19] op_sel_hi:[0,1,1]
	v_pk_fma_f32 v[98:99], v[2:3], v[98:99], v[4:5] op_sel_hi:[0,1,1]
	v_pk_fma_f32 v[4:5], v[2:3], v[100:101], v[6:7] op_sel_hi:[0,1,1]
	s_waitcnt lgkmcnt(0)
	v_add_f32_e32 v102, v102, v103
	ds_bpermute_b32 v103, v92, v102
	s_waitcnt lgkmcnt(0)
	v_add_f32_e32 v102, v102, v103
	s_waitcnt vmcnt(0)
	v_fmac_f32_e32 v97, v2, v102
	v_max_f32_e64 v97, |v97|, 1.0
	v_div_scale_f32 v102, s[16:17], v97, v97, 1.0
	v_rcp_f32_e32 v103, v102
	s_mov_b64 s[16:17], 0x80
	v_fma_f32 v104, -v102, v103, 1.0
	v_fmac_f32_e32 v103, v104, v103
	v_div_scale_f32 v104, vcc, 1.0, v97, 1.0
	v_mul_f32_e32 v105, v104, v103
	v_fma_f32 v106, -v102, v105, v104
	v_fmac_f32_e32 v105, v106, v103
	v_fma_f32 v102, -v102, v105, v104
	v_div_fmas_f32 v102, v102, v103, v105
	v_div_fixup_f32 v102, v102, v97, 1.0
	v_pk_mul_f32 v[106:107], v[32:33], v[102:103] op_sel_hi:[1,0]
	v_pk_fma_f32 v[32:33], v[2:3], v[118:119], v[28:29] op_sel_hi:[0,1,1]
	v_pk_fma_f32 v[28:29], v[2:3], v[120:121], v[30:31] op_sel_hi:[0,1,1]
	v_pk_mul_f32 v[30:31], v[32:33], v[102:103] op_sel_hi:[1,0]
	v_pk_mul_f32 v[104:105], v[34:35], v[102:103] op_sel_hi:[1,0]
	v_pk_mul_f32 v[28:29], v[28:29], v[102:103] op_sel_hi:[1,0]
	v_mov_b32_e32 v34, v107
	v_mov_b32_e32 v35, v31
	v_mov_b32_e32 v32, v106
	v_mov_b32_e32 v33, v30
	v_pk_mul_f32 v[34:35], v[34:35], v[34:35]
	v_mov_b32_e32 v108, v105
	v_mov_b32_e32 v109, v29
	v_pk_fma_f32 v[32:33], v[32:33], v[32:33], v[34:35]
	v_mov_b32_e32 v34, v104
	v_mov_b32_e32 v35, v28
	v_pk_mul_f32 v[108:109], v[108:109], v[108:109]
	v_pk_mul_f32 v[16:17], v[16:17], v[102:103] op_sel_hi:[1,0]
	v_pk_fma_f32 v[34:35], v[34:35], v[34:35], v[108:109]
	v_pk_mul_f32 v[18:19], v[112:113], v[102:103] op_sel_hi:[1,0]
	v_pk_add_f32 v[32:33], v[32:33], v[34:35]
	v_pk_fma_f32 v[34:35], v[2:3], v[124:125], v[26:27] op_sel_hi:[0,1,1]
	v_pk_mul_f32 v[26:27], v[24:25], v[102:103] op_sel_hi:[1,0]
	v_pk_mul_f32 v[24:25], v[34:35], v[102:103] op_sel_hi:[1,0]
	v_pk_mul_f32 v[108:109], v[26:27], v[26:27]
	v_pk_mul_f32 v[34:35], v[24:25], v[24:25]
	v_pk_add_f32 v[32:33], v[32:33], v[32:33] op_sel_hi:[0,1]
	v_pk_mov_b32 v[110:111], v[108:109], v[34:35] op_sel:[1,0]
	v_mov_b32_e32 v109, v35
	v_pk_add_f32 v[34:35], v[110:111], v[108:109]
	v_pk_fma_f32 v[108:109], v[2:3], v[126:127], v[20:21] op_sel_hi:[0,1,1]
	v_pk_fma_f32 v[20:21], v[2:3], v[128:129], v[22:23] op_sel_hi:[0,1,1]
	v_pk_mul_f32 v[22:23], v[108:109], v[102:103] op_sel_hi:[1,0]
	v_pk_mul_f32 v[20:21], v[20:21], v[102:103] op_sel_hi:[1,0]
	v_mul_f32_e32 v32, v22, v22
	v_pk_add_f32 v[34:35], v[34:35], v[34:35] op_sel_hi:[0,1]
	v_pk_fma_f32 v[108:109], v[22:23], v[22:23], v[32:33] op_sel_hi:[1,1,0]
	v_mul_f32_e32 v32, v20, v20
	v_pk_fma_f32 v[110:111], v[20:21], v[20:21], v[32:33] op_sel_hi:[1,1,0]
	v_mul_f32_e32 v34, v16, v16
	v_mul_f32_e32 v32, v17, v17
	v_mul_f32_e32 v108, v18, v18
	v_mul_f32_e32 v110, v19, v19
	v_pk_add_f32 v[32:33], v[34:35], v[32:33]
	v_pk_fma_f32 v[34:35], v[2:3], v[136:137], v[14:15] op_sel_hi:[0,1,1]
	v_pk_add_f32 v[108:109], v[108:109], v[110:111]
	v_pk_mul_f32 v[14:15], v[12:13], v[102:103] op_sel_hi:[1,0]
	v_pk_mul_f32 v[12:13], v[34:35], v[102:103] op_sel_hi:[1,0]
	v_pk_add_f32 v[32:33], v[108:109], v[32:33]
	v_pk_mul_f32 v[34:35], v[12:13], v[12:13]
	v_pk_mul_f32 v[108:109], v[14:15], v[14:15]
	v_pk_add_f32 v[32:33], v[32:33], v[32:33] op_sel_hi:[0,1]
	v_pk_mov_b32 v[110:111], v[108:109], v[34:35] op_sel:[1,0]
	v_mov_b32_e32 v109, v35
	v_pk_add_f32 v[34:35], v[110:111], v[108:109]
	v_pk_fma_f32 v[108:109], v[2:3], v[138:139], v[8:9] op_sel_hi:[0,1,1]
	v_pk_fma_f32 v[8:9], v[2:3], v[140:141], v[10:11] op_sel_hi:[0,1,1]
	v_pk_mul_f32 v[10:11], v[108:109], v[102:103] op_sel_hi:[1,0]
	v_pk_mul_f32 v[8:9], v[8:9], v[102:103] op_sel_hi:[1,0]
	v_mul_f32_e32 v32, v10, v10
	v_pk_fma_f32 v[108:109], v[10:11], v[10:11], v[32:33] op_sel_hi:[1,1,0]
	v_mul_f32_e32 v32, v8, v8
	v_pk_add_f32 v[34:35], v[34:35], v[34:35] op_sel_hi:[0,1]
	v_pk_fma_f32 v[110:111], v[8:9], v[8:9], v[32:33] op_sel_hi:[1,1,0]
	v_pk_mul_f32 v[4:5], v[4:5], v[102:103] op_sel_hi:[1,0]
	v_pk_mul_f32 v[6:7], v[98:99], v[102:103] op_sel_hi:[1,0]
	v_mul_f32_e32 v34, v4, v4
	v_mul_f32_e32 v108, v6, v6
	v_mul_f32_e32 v110, v7, v7
	v_mul_f32_e32 v32, v5, v5
	v_pk_add_f32 v[98:99], v[108:109], v[110:111]
	v_pk_add_f32 v[32:33], v[34:35], v[32:33]
	v_lshlrev_b32_e32 v97, 16, v86
	v_pk_add_f32 v[32:33], v[98:99], v[32:33]
	v_and_b32_e32 v86, 0xffff0000, v86
	v_add_f32_e32 v2, v32, v33
	ds_bpermute_b32 v32, v91, v2
	v_mul_f32_e32 v86, 0xbfb8aa3b, v86
	v_exp_f32_e32 v86, v86
	v_mul_f32_e32 v97, 0xbfb8aa3b, v97
	v_exp_f32_e32 v97, v97
	s_waitcnt lgkmcnt(0)
	v_add_f32_e32 v2, v2, v32
	ds_bpermute_b32 v32, v92, v2
	v_add_f32_e32 v86, 1.0, v86
	v_rcp_f32_e32 v99, v86
	v_lshlrev_b32_e32 v86, 16, v87
	v_and_b32_e32 v87, 0xffff0000, v87
	s_waitcnt lgkmcnt(0)
	v_add_f32_e32 v2, v2, v32
	v_fmamk_f32 v2, v2, 0x3c000000, v172
	v_cmp_gt_f32_e32 vcc, s33, v2
	v_mul_f32_e32 v32, 0x4b800000, v2
	v_mul_f32_e32 v86, 0xbfb8aa3b, v86
	v_cndmask_b32_e32 v2, v2, v32, vcc
	v_rsq_f32_e32 v2, v2
	v_mul_f32_e32 v87, 0xbfb8aa3b, v87
	v_exp_f32_e32 v86, v86
	v_exp_f32_e32 v87, v87
	v_mul_f32_e32 v32, 0x45800000, v2
	v_cndmask_b32_e32 v2, v2, v32, vcc
	v_add_f32_e32 v97, 1.0, v97
	v_rcp_f32_e32 v98, v97
	v_add_f32_e32 v86, 1.0, v86
	v_add_f32_e32 v87, 1.0, v87
	v_pk_mul_f32 v[100:101], v[106:107], v[2:3] op_sel_hi:[1,0]
	v_rcp_f32_e32 v86, v86
	v_rcp_f32_e32 v87, v87
	v_pk_mul_f32 v[30:31], v[30:31], v[2:3] op_sel_hi:[1,0]
	v_pk_mul_f32 v[28:29], v[28:29], v[2:3] op_sel_hi:[1,0]
	v_pk_mul_f32 v[26:27], v[26:27], v[2:3] op_sel_hi:[1,0]
	v_pk_mul_f32 v[24:25], v[24:25], v[2:3] op_sel_hi:[1,0]
	v_pk_mul_f32 v[22:23], v[22:23], v[2:3] op_sel_hi:[1,0]
	v_pk_mul_f32 v[20:21], v[20:21], v[2:3] op_sel_hi:[1,0]
	v_pk_mul_f32 v[18:19], v[18:19], v[2:3] op_sel_hi:[1,0]
	v_pk_mul_f32 v[16:17], v[16:17], v[2:3] op_sel_hi:[1,0]
	v_pk_mul_f32 v[14:15], v[14:15], v[2:3] op_sel_hi:[1,0]
	v_pk_mul_f32 v[12:13], v[12:13], v[2:3] op_sel_hi:[1,0]
	v_pk_mul_f32 v[10:11], v[10:11], v[2:3] op_sel_hi:[1,0]
	v_pk_mul_f32 v[8:9], v[8:9], v[2:3] op_sel_hi:[1,0]
	v_pk_mul_f32 v[6:7], v[6:7], v[2:3] op_sel_hi:[1,0]
	v_pk_mul_f32 v[4:5], v[4:5], v[2:3] op_sel_hi:[1,0]
	s_andn2_b64 vcc, exec, s[14:15]
	s_mov_b64 s[14:15], 0
	s_waitcnt vmcnt(0)
	v_mov_b64_e32 v[32:33], v[184:185]
	v_mov_b64_e32 v[34:35], v[186:187]
	v_pk_mul_f32 v[32:33], v[32:33], v[100:101]
	s_nop 0
	v_pk_mul_f32 v[32:33], v[98:99], v[32:33]
	v_pk_mul_f32 v[98:99], v[104:105], v[2:3] op_sel_hi:[1,0]
	v_cvt_pk_bf16_f32 v32, v32, v33
	v_pk_mul_f32 v[34:35], v[34:35], v[98:99]
	s_nop 0
	v_pk_mul_f32 v[34:35], v[86:87], v[34:35]
	s_nop 0
	v_cvt_pk_bf16_f32 v33, v34, v35
	v_lshl_add_u64 v[34:35], v[68:69], 0, v[84:85]
	global_store_dwordx2 v[34:35], v[32:33], off
	v_lshlrev_b32_e32 v32, 16, v82
	v_and_b32_e32 v33, 0xffff0000, v82
	v_mul_f32_e32 v32, 0xbfb8aa3b, v32
	v_mul_f32_e32 v33, 0xbfb8aa3b, v33
	v_exp_f32_e32 v32, v32
	v_exp_f32_e32 v33, v33
	v_add_f32_e32 v32, 1.0, v32
	v_add_f32_e32 v33, 1.0, v33
	v_rcp_f32_e32 v32, v32
	v_rcp_f32_e32 v33, v33
	v_mov_b64_e32 v[84:85], v[188:189]
	v_mov_b64_e32 v[86:87], v[190:191]
	v_pk_mul_f32 v[30:31], v[84:85], v[30:31]
	s_nop 0
	v_pk_mul_f32 v[30:31], v[32:33], v[30:31]
	v_lshlrev_b32_e32 v32, 16, v83
	v_and_b32_e32 v33, 0xffff0000, v83
	v_mul_f32_e32 v32, 0xbfb8aa3b, v32
	v_mul_f32_e32 v33, 0xbfb8aa3b, v33
	v_exp_f32_e32 v32, v32
	v_exp_f32_e32 v33, v33
	v_pk_mul_f32 v[28:29], v[86:87], v[28:29]
	v_cvt_pk_bf16_f32 v30, v30, v31
	v_add_f32_e32 v32, 1.0, v32
	v_add_f32_e32 v33, 1.0, v33
	v_rcp_f32_e32 v32, v32
	v_rcp_f32_e32 v33, v33
	s_nop 0
	v_pk_mul_f32 v[28:29], v[32:33], v[28:29]
	s_nop 0
	v_cvt_pk_bf16_f32 v31, v28, v29
	global_store_dwordx2 v[34:35], v[30:31], off offset:32
	v_lshlrev_b32_e32 v32, 16, v80
	v_and_b32_e32 v33, 0xffff0000, v80
	v_mul_f32_e32 v32, 0xbfb8aa3b, v32
	v_mul_f32_e32 v33, 0xbfb8aa3b, v33
	v_exp_f32_e32 v32, v32
	v_exp_f32_e32 v33, v33
	v_add_f32_e32 v32, 1.0, v32
	v_add_f32_e32 v33, 1.0, v33
	v_rcp_f32_e32 v32, v32
	v_rcp_f32_e32 v33, v33
	v_mov_b64_e32 v[28:29], v[192:193]
	v_mov_b64_e32 v[30:31], v[194:195]
	v_pk_mul_f32 v[26:27], v[28:29], v[26:27]
	v_lshlrev_b32_e32 v28, 16, v81
	v_and_b32_e32 v29, 0xffff0000, v81
	v_mul_f32_e32 v28, 0xbfb8aa3b, v28
	v_mul_f32_e32 v29, 0xbfb8aa3b, v29
	v_exp_f32_e32 v28, v28
	v_exp_f32_e32 v29, v29
	v_pk_mul_f32 v[24:25], v[30:31], v[24:25]
	v_pk_mul_f32 v[26:27], v[32:33], v[26:27]
	v_add_f32_e32 v28, 1.0, v28
	v_add_f32_e32 v29, 1.0, v29
	v_rcp_f32_e32 v28, v28
	v_rcp_f32_e32 v29, v29
	v_cvt_pk_bf16_f32 v26, v26, v27
	v_pk_mul_f32 v[24:25], v[28:29], v[24:25]
	s_nop 0
	v_cvt_pk_bf16_f32 v27, v24, v25
	global_store_dwordx2 v[34:35], v[26:27], off offset:64
	v_lshlrev_b32_e32 v28, 16, v78
	v_and_b32_e32 v29, 0xffff0000, v78
	v_mul_f32_e32 v28, 0xbfb8aa3b, v28
	v_mul_f32_e32 v29, 0xbfb8aa3b, v29
	v_exp_f32_e32 v28, v28
	v_exp_f32_e32 v29, v29
	v_add_f32_e32 v28, 1.0, v28
	v_add_f32_e32 v29, 1.0, v29
	v_rcp_f32_e32 v28, v28
	v_rcp_f32_e32 v29, v29
	v_mov_b64_e32 v[24:25], v[196:197]
	v_mov_b64_e32 v[26:27], v[198:199]
	v_pk_mul_f32 v[22:23], v[24:25], v[22:23]
	v_lshlrev_b32_e32 v24, 16, v79
	v_and_b32_e32 v25, 0xffff0000, v79
	v_mul_f32_e32 v24, 0xbfb8aa3b, v24
	v_mul_f32_e32 v25, 0xbfb8aa3b, v25
	v_exp_f32_e32 v24, v24
	v_exp_f32_e32 v25, v25
	v_pk_mul_f32 v[20:21], v[26:27], v[20:21]
	v_pk_mul_f32 v[22:23], v[28:29], v[22:23]
	v_add_f32_e32 v24, 1.0, v24
	v_add_f32_e32 v25, 1.0, v25
	v_rcp_f32_e32 v24, v24
	v_rcp_f32_e32 v25, v25
	v_cvt_pk_bf16_f32 v22, v22, v23
	v_pk_mul_f32 v[20:21], v[24:25], v[20:21]
	s_nop 0
	v_cvt_pk_bf16_f32 v23, v20, v21
	global_store_dwordx2 v[34:35], v[22:23], off offset:96
	v_lshlrev_b32_e32 v24, 16, v76
	v_and_b32_e32 v25, 0xffff0000, v76
	v_mul_f32_e32 v24, 0xbfb8aa3b, v24
	v_mul_f32_e32 v25, 0xbfb8aa3b, v25
	v_exp_f32_e32 v24, v24
	v_exp_f32_e32 v25, v25
	v_add_f32_e32 v24, 1.0, v24
	v_add_f32_e32 v25, 1.0, v25
	v_rcp_f32_e32 v24, v24
	v_rcp_f32_e32 v25, v25
	v_mov_b64_e32 v[20:21], v[200:201]
	v_mov_b64_e32 v[22:23], v[202:203]
	v_pk_mul_f32 v[18:19], v[20:21], v[18:19]
	v_lshlrev_b32_e32 v20, 16, v77
	v_and_b32_e32 v21, 0xffff0000, v77
	v_mul_f32_e32 v20, 0xbfb8aa3b, v20
	v_mul_f32_e32 v21, 0xbfb8aa3b, v21
	v_exp_f32_e32 v20, v20
	v_exp_f32_e32 v21, v21
	v_pk_mul_f32 v[16:17], v[22:23], v[16:17]
	v_pk_mul_f32 v[18:19], v[24:25], v[18:19]
	v_add_f32_e32 v20, 1.0, v20
	v_add_f32_e32 v21, 1.0, v21
	v_rcp_f32_e32 v20, v20
	v_rcp_f32_e32 v21, v21
	v_cvt_pk_bf16_f32 v18, v18, v19
	v_pk_mul_f32 v[16:17], v[20:21], v[16:17]
	s_nop 0
	v_cvt_pk_bf16_f32 v19, v16, v17
	global_store_dwordx2 v[34:35], v[18:19], off offset:128
	v_lshlrev_b32_e32 v20, 16, v74
	v_and_b32_e32 v21, 0xffff0000, v74
	v_mul_f32_e32 v20, 0xbfb8aa3b, v20
	v_mul_f32_e32 v21, 0xbfb8aa3b, v21
	v_exp_f32_e32 v20, v20
	v_exp_f32_e32 v21, v21
	v_add_f32_e32 v20, 1.0, v20
	v_add_f32_e32 v21, 1.0, v21
	v_rcp_f32_e32 v20, v20
	v_rcp_f32_e32 v21, v21
	v_mov_b64_e32 v[16:17], v[204:205]
	v_mov_b64_e32 v[18:19], v[206:207]
	v_pk_mul_f32 v[14:15], v[16:17], v[14:15]
	v_lshlrev_b32_e32 v16, 16, v75
	v_and_b32_e32 v17, 0xffff0000, v75
	v_mul_f32_e32 v16, 0xbfb8aa3b, v16
	v_mul_f32_e32 v17, 0xbfb8aa3b, v17
	v_exp_f32_e32 v16, v16
	v_exp_f32_e32 v17, v17
	v_pk_mul_f32 v[12:13], v[18:19], v[12:13]
	v_pk_mul_f32 v[14:15], v[20:21], v[14:15]
	v_add_f32_e32 v16, 1.0, v16
	v_add_f32_e32 v17, 1.0, v17
	v_rcp_f32_e32 v16, v16
	v_rcp_f32_e32 v17, v17
	v_cvt_pk_bf16_f32 v14, v14, v15
	v_pk_mul_f32 v[12:13], v[16:17], v[12:13]
	s_nop 0
	v_cvt_pk_bf16_f32 v15, v12, v13
	global_store_dwordx2 v[34:35], v[14:15], off offset:160
	v_lshlrev_b32_e32 v16, 16, v72
	v_and_b32_e32 v17, 0xffff0000, v72
	v_mul_f32_e32 v16, 0xbfb8aa3b, v16
	v_mul_f32_e32 v17, 0xbfb8aa3b, v17
	v_exp_f32_e32 v16, v16
	v_exp_f32_e32 v17, v17
	v_add_f32_e32 v16, 1.0, v16
	v_add_f32_e32 v17, 1.0, v17
	v_rcp_f32_e32 v16, v16
	v_rcp_f32_e32 v17, v17
	v_mov_b64_e32 v[12:13], v[230:231]
	v_mov_b64_e32 v[14:15], v[232:233]
	v_pk_mul_f32 v[10:11], v[12:13], v[10:11]
	v_lshlrev_b32_e32 v12, 16, v73
	v_and_b32_e32 v13, 0xffff0000, v73
	v_mul_f32_e32 v12, 0xbfb8aa3b, v12
	v_mul_f32_e32 v13, 0xbfb8aa3b, v13
	v_exp_f32_e32 v12, v12
	v_exp_f32_e32 v13, v13
	v_pk_mul_f32 v[8:9], v[14:15], v[8:9]
	v_pk_mul_f32 v[10:11], v[16:17], v[10:11]
	v_add_f32_e32 v12, 1.0, v12
	v_add_f32_e32 v13, 1.0, v13
	v_rcp_f32_e32 v12, v12
	v_rcp_f32_e32 v13, v13
	v_cvt_pk_bf16_f32 v10, v10, v11
	v_pk_mul_f32 v[8:9], v[12:13], v[8:9]
	s_nop 0
	v_cvt_pk_bf16_f32 v11, v8, v9
	global_store_dwordx2 v[34:35], v[10:11], off offset:192
	v_lshlrev_b32_e32 v12, 16, v70
	v_and_b32_e32 v13, 0xffff0000, v70
	v_mul_f32_e32 v12, 0xbfb8aa3b, v12
	v_mul_f32_e32 v13, 0xbfb8aa3b, v13
	v_exp_f32_e32 v12, v12
	v_exp_f32_e32 v13, v13
	v_add_f32_e32 v12, 1.0, v12
	v_add_f32_e32 v13, 1.0, v13
	v_rcp_f32_e32 v12, v12
	v_rcp_f32_e32 v13, v13
	v_mov_b64_e32 v[8:9], v[234:235]
	v_mov_b64_e32 v[10:11], v[236:237]
	v_pk_mul_f32 v[6:7], v[8:9], v[6:7]
	v_lshlrev_b32_e32 v8, 16, v71
	v_and_b32_e32 v9, 0xffff0000, v71
	v_mul_f32_e32 v8, 0xbfb8aa3b, v8
	v_mul_f32_e32 v9, 0xbfb8aa3b, v9
	v_exp_f32_e32 v8, v8
	v_exp_f32_e32 v9, v9
	v_pk_mul_f32 v[4:5], v[10:11], v[4:5]
	v_pk_mul_f32 v[6:7], v[12:13], v[6:7]
	v_add_f32_e32 v8, 1.0, v8
	v_add_f32_e32 v9, 1.0, v9
	v_rcp_f32_e32 v8, v8
	v_rcp_f32_e32 v9, v9
	v_cvt_pk_bf16_f32 v6, v6, v7
	v_pk_mul_f32 v[4:5], v[8:9], v[4:5]
	s_nop 0
	v_cvt_pk_bf16_f32 v7, v4, v5
	global_store_dwordx2 v[34:35], v[6:7], off offset:224
	s_cbranch_vccz .LBB0_76
	v_readlane_b32 s14, v252, 7
	v_readlane_b32 s15, v252, 8
	s_load_dword s13, s[14:15], 0x0
	s_waitcnt lgkmcnt(0)
	s_add_i32 s12, s12, s13
	s_cmpk_gt_i32 s12, 0xff
	s_cbranch_scc0 .LBB0_73

.LBB0_218:
	v_lshl_add_u64 v[4:5], v[54:55], 0, s[8:9]
	v_mad_u64_u32 v[8:9], s[10:11], v4, s12, v[56:57]
	v_mov_b32_e32 v2, v9
	v_mad_u64_u32 v[10:11], s[10:11], v5, s12, v[2:3]
	v_mov_b32_e32 v9, v10
	s_mov_b32 s5, 0x38000
	v_add_co_u32_e32 v114, vcc, s5, v8
	s_mov_b32 s5, 0x70000
	s_nop 0
	v_addc_co_u32_e32 v115, vcc, 0, v10, vcc
	v_add_co_u32_e32 v116, vcc, s5, v8
	s_mov_b32 s5, 0xa8000
	s_nop 0
	v_addc_co_u32_e32 v117, vcc, 0, v10, vcc
	v_add_co_u32_e32 v118, vcc, s5, v8
	s_nop 1
	v_addc_co_u32_e32 v119, vcc, 0, v10, vcc
	global_load_dwordx4 v[120:123], v[8:9], off
	global_load_dwordx4 v[124:127], v[114:115], off
	global_load_dwordx4 v[128:131], v[116:117], off
	global_load_dwordx4 v[132:135], v[118:119], off
	v_lshl_add_u64 v[4:5], v[58:59], 0, s[8:9]
	v_mad_u64_u32 v[68:69], s[8:9], v4, s12, v[64:65]
	v_mov_b32_e32 v2, v69
	v_lshlrev_b64 v[84:85], 11, v[4:5]
	v_mad_u64_u32 v[4:5], s[8:9], v5, s12, v[2:3]
	v_lshl_add_u64 v[32:33], v[60:61], 0, v[84:85]
	v_mov_b32_e32 v69, v4
	global_load_dwordx4 v[24:27], v[32:33], off
	global_load_dwordx2 v[86:87], v[68:69], off offset:3072
	global_load_dwordx4 v[28:31], v[32:33], off offset:64
	global_load_dwordx2 v[80:81], v[68:69], off offset:3104
	global_load_dwordx4 v[20:23], v[32:33], off offset:128
	global_load_dwordx2 v[78:79], v[68:69], off offset:3136
	global_load_dwordx4 v[12:15], v[32:33], off offset:192
	global_load_dwordx2 v[76:77], v[68:69], off offset:3168
	global_load_dwordx4 v[16:19], v[32:33], off offset:256
	global_load_dwordx2 v[74:75], v[68:69], off offset:3200
	global_load_dwordx4 v[8:11], v[32:33], off offset:320
	global_load_dwordx2 v[72:73], v[68:69], off offset:3232
	global_load_dwordx4 v[4:7], v[32:33], off offset:384
	global_load_dwordx2 v[70:71], v[68:69], off offset:3264
	s_nop 0
	global_load_dwordx4 v[32:35], v[32:33], off offset:448
	s_nop 0
	global_load_dwordx2 v[68:69], v[68:69], off offset:3296
	s_waitcnt lgkmcnt(0)
	s_barrier
	s_waitcnt vmcnt(19)
	ds_write_b128 v93, v[120:123] offset:34816
	s_waitcnt vmcnt(18)
	ds_write_b128 v93, v[124:127] offset:43520
	s_waitcnt vmcnt(17)
	ds_write_b128 v93, v[128:131] offset:52224
	s_waitcnt vmcnt(16)
	ds_write_b128 v93, v[132:135] offset:60928
	s_waitcnt lgkmcnt(0)
	s_barrier
	ds_read_b128 v[94:97], v91 offset:34816
	ds_read_b128 v[98:101], v91 offset:34880
	ds_read_b128 v[102:105], v91 offset:34944
	ds_read_b128 v[106:109], v91 offset:35008
	ds_read_b128 v[142:145], v92
	ds_read_b128 v[146:149], v92 offset:64
	ds_read_b128 v[150:153], v92 offset:128
	ds_read_b128 v[154:157], v92 offset:192
	ds_read_b128 v[158:161], v92 offset:4352
	ds_read_b128 v[162:165], v92 offset:4416
	ds_read_b128 v[166:169], v92 offset:4480
	s_waitcnt lgkmcnt(6)
	v_mfma_f32_16x16x32_bf16 v[110:113], v[142:145], v[94:97], 0
	ds_read_b128 v[238:241], v92 offset:4544
	s_waitcnt lgkmcnt(6)
	v_mfma_f32_16x16x32_bf16 v[110:113], v[146:149], v[98:101], v[110:113]
	ds_read_b128 v[142:145], v92 offset:8704
	s_waitcnt lgkmcnt(6)
	v_mfma_f32_16x16x32_bf16 v[110:113], v[150:153], v[102:105], v[110:113]
	ds_read_b128 v[146:149], v92 offset:8768
	s_waitcnt lgkmcnt(6)
	v_mfma_f32_16x16x32_bf16 v[110:113], v[154:157], v[106:109], v[110:113]
	ds_read_b128 v[150:153], v92 offset:8832
	s_waitcnt lgkmcnt(6)
	v_mfma_f32_16x16x32_bf16 v[114:117], v[158:161], v[94:97], 0
	ds_read_b128 v[154:157], v92 offset:8896
	s_waitcnt lgkmcnt(6)
	v_mfma_f32_16x16x32_bf16 v[114:117], v[162:165], v[98:101], v[114:117]
	ds_read_b128 v[158:161], v92 offset:13056
	s_waitcnt lgkmcnt(6)
	v_mfma_f32_16x16x32_bf16 v[114:117], v[166:169], v[102:105], v[114:117]
	ds_read_b128 v[162:165], v92 offset:13120
	s_waitcnt lgkmcnt(6)
	v_mfma_f32_16x16x32_bf16 v[114:117], v[238:241], v[106:109], v[114:117]
	ds_read_b128 v[166:169], v92 offset:13184
	s_waitcnt lgkmcnt(6)
	v_mfma_f32_16x16x32_bf16 v[118:121], v[142:145], v[94:97], 0
	ds_read_b128 v[238:241], v92 offset:13248
	s_waitcnt lgkmcnt(6)
	v_mfma_f32_16x16x32_bf16 v[118:121], v[146:149], v[98:101], v[118:121]
	ds_read_b128 v[142:145], v92 offset:17408
	s_waitcnt lgkmcnt(6)
	v_mfma_f32_16x16x32_bf16 v[118:121], v[150:153], v[102:105], v[118:121]
	ds_read_b128 v[146:149], v92 offset:17472
	s_waitcnt lgkmcnt(6)
	v_mfma_f32_16x16x32_bf16 v[118:121], v[154:157], v[106:109], v[118:121]
	ds_read_b128 v[150:153], v92 offset:17536
	s_waitcnt lgkmcnt(6)
	v_mfma_f32_16x16x32_bf16 v[122:125], v[158:161], v[94:97], 0
	ds_read_b128 v[154:157], v92 offset:17600
	s_waitcnt lgkmcnt(6)
	v_mfma_f32_16x16x32_bf16 v[122:125], v[162:165], v[98:101], v[122:125]
	ds_read_b128 v[158:161], v92 offset:21760
	s_waitcnt lgkmcnt(6)
	v_mfma_f32_16x16x32_bf16 v[122:125], v[166:169], v[102:105], v[122:125]
	ds_read_b128 v[162:165], v92 offset:21824
	s_waitcnt lgkmcnt(6)
	v_mfma_f32_16x16x32_bf16 v[122:125], v[238:241], v[106:109], v[122:125]
	ds_read_b128 v[166:169], v92 offset:21888
	s_waitcnt lgkmcnt(6)
	v_mfma_f32_16x16x32_bf16 v[126:129], v[142:145], v[94:97], 0
	ds_read_b128 v[238:241], v92 offset:21952
	s_waitcnt lgkmcnt(6)
	v_mfma_f32_16x16x32_bf16 v[126:129], v[146:149], v[98:101], v[126:129]
	ds_read_b128 v[142:145], v92 offset:26112
	s_waitcnt lgkmcnt(6)
	v_mfma_f32_16x16x32_bf16 v[126:129], v[150:153], v[102:105], v[126:129]
	ds_read_b128 v[146:149], v92 offset:26176
	s_waitcnt lgkmcnt(6)
	v_mfma_f32_16x16x32_bf16 v[126:129], v[154:157], v[106:109], v[126:129]
	ds_read_b128 v[150:153], v92 offset:26240
	s_waitcnt lgkmcnt(6)
	v_mfma_f32_16x16x32_bf16 v[130:133], v[158:161], v[94:97], 0
	ds_read_b128 v[154:157], v92 offset:26304
	s_waitcnt lgkmcnt(6)
	v_mfma_f32_16x16x32_bf16 v[130:133], v[162:165], v[98:101], v[130:133]
	ds_read_b128 v[158:161], v92 offset:30464
	s_waitcnt lgkmcnt(6)
	v_mfma_f32_16x16x32_bf16 v[130:133], v[166:169], v[102:105], v[130:133]
	ds_read_b128 v[162:165], v92 offset:30528
	s_waitcnt lgkmcnt(6)
	v_mfma_f32_16x16x32_bf16 v[130:133], v[238:241], v[106:109], v[130:133]
	ds_read_b128 v[166:169], v92 offset:30592
	s_waitcnt lgkmcnt(6)
	v_mfma_f32_16x16x32_bf16 v[134:137], v[142:145], v[94:97], 0
	ds_read_b128 v[238:241], v92 offset:30656
	s_waitcnt lgkmcnt(6)
	v_mfma_f32_16x16x32_bf16 v[134:137], v[146:149], v[98:101], v[134:137]
	s_waitcnt lgkmcnt(5)
	v_mfma_f32_16x16x32_bf16 v[134:137], v[150:153], v[102:105], v[134:137]
	s_waitcnt lgkmcnt(4)
	v_mfma_f32_16x16x32_bf16 v[134:137], v[154:157], v[106:109], v[134:137]
	s_waitcnt lgkmcnt(3)
	v_mfma_f32_16x16x32_bf16 v[94:97], v[158:161], v[94:97], 0
	s_waitcnt lgkmcnt(2)
	v_mfma_f32_16x16x32_bf16 v[94:97], v[162:165], v[98:101], v[94:97]
	s_waitcnt lgkmcnt(1)
	v_mfma_f32_16x16x32_bf16 v[94:97], v[166:169], v[102:105], v[94:97]
	s_waitcnt lgkmcnt(0)
	v_mfma_f32_16x16x32_bf16 v[94:97], v[238:241], v[106:109], v[94:97]
	s_nop 7
	s_mov_b64 s[8:9], 0x80
	s_waitcnt vmcnt(15)
	v_pk_add_f32 v[24:25], v[24:25], v[110:111]
	s_nop 0
	s_waitcnt vmcnt(13)
	v_pk_add_f32 v[82:83], v[28:29], v[114:115]
	s_nop 0
	v_add_f32_e64 v30, v30, v116
	v_add_f32_e64 v31, v31, v117
	v_mov_b32_e32 v28, v25
	v_mov_b32_e32 v29, v83
	s_nop 0
	v_pk_mul_f32 v[28:29], v[28:29], v[28:29]
	s_nop 0
	s_waitcnt vmcnt(7)
	v_pk_add_f32 v[16:17], v[16:17], v[126:127]
	s_nop 0
	v_mul_f32_e32 v2, v16, v16
	s_nop 0
	v_pk_add_f32 v[18:19], v[18:19], v[128:129]
	s_nop 0
	v_mul_f32_e32 v104, v17, v17
	v_mul_f32_e32 v105, v18, v18
	v_add_f32_e64 v98, v26, v112
	v_add_f32_e64 v99, v27, v113
	v_mov_b32_e32 v26, v24
	v_mov_b32_e32 v27, v82
	v_mov_b32_e32 v100, v99
	v_mov_b32_e32 v101, v31
	v_pk_fma_f32 v[26:27], v[26:27], v[26:27], v[28:29]
	v_mov_b32_e32 v28, v98
	v_mov_b32_e32 v29, v30
	v_pk_mul_f32 v[100:101], v[100:101], v[100:101]
	v_mul_f32_e32 v106, v19, v19
	v_pk_fma_f32 v[28:29], v[28:29], v[28:29], v[100:101]
	s_nop 0
	v_pk_add_f32 v[100:101], v[26:27], v[28:29]
	v_pk_add_f32 v[26:27], v[22:23], v[120:121]
	v_pk_add_f32 v[28:29], v[20:21], v[118:119]
	v_pk_mul_f32 v[20:21], v[26:27], v[26:27]
	v_pk_mul_f32 v[22:23], v[28:29], v[28:29]
	s_nop 0
	v_pk_mov_b32 v[102:103], v[22:23], v[20:21] op_sel:[1,0]
	v_mov_b32_e32 v23, v21
	v_pk_add_f32 v[102:103], v[102:103], v[22:23]
	v_pk_add_f32 v[20:21], v[14:15], v[124:125]
	v_pk_add_f32 v[22:23], v[12:13], v[122:123]
	v_pk_add_f32 v[12:13], v[100:101], v[100:101] op_sel:[0,1] op_sel_hi:[1,0]
	v_pk_add_f32 v[14:15], v[102:103], v[102:103] op_sel:[0,1] op_sel_hi:[1,0]
	v_mov_b32_e32 v13, v2
	v_mov_b32_e32 v15, v104
	v_mul_f32_e32 v2, v23, v23
	v_pk_add_f32 v[12:13], v[12:13], v[14:15]
	v_pk_fma_f32 v[14:15], v[22:23], v[22:23], v[2:3] op_sel_hi:[1,1,0]
	v_mul_f32_e32 v2, v21, v21
	v_pk_fma_f32 v[100:101], v[20:21], v[20:21], v[2:3] op_sel_hi:[1,1,0]
	v_mov_b32_e32 v15, v105
	v_mov_b32_e32 v101, v106
	v_pk_add_f32 v[14:15], v[14:15], v[100:101]
	s_nop 0
	v_pk_add_f32 v[100:101], v[12:13], v[14:15]
	s_waitcnt vmcnt(5)
	v_pk_add_f32 v[12:13], v[10:11], v[132:133]
	v_pk_add_f32 v[14:15], v[8:9], v[130:131]
	v_pk_mul_f32 v[8:9], v[12:13], v[12:13]
	v_pk_mul_f32 v[10:11], v[14:15], v[14:15]
	s_nop 0
	v_pk_mov_b32 v[102:103], v[10:11], v[8:9] op_sel:[1,0]
	v_mov_b32_e32 v11, v9
	v_pk_add_f32 v[102:103], v[102:103], v[10:11]
	s_waitcnt vmcnt(3)
	v_pk_add_f32 v[8:9], v[6:7], v[136:137]
	s_waitcnt vmcnt(1)
	v_pk_add_f32 v[6:7], v[32:33], v[94:95]
	v_pk_add_f32 v[10:11], v[4:5], v[134:135]
	v_pk_add_f32 v[4:5], v[34:35], v[96:97]
	v_mul_f32_e32 v2, v6, v6
	v_mul_f32_e32 v94, v7, v7
	v_pk_add_f32 v[32:33], v[100:101], v[100:101] op_sel:[0,1] op_sel_hi:[1,0]
	v_pk_add_f32 v[34:35], v[102:103], v[102:103] op_sel:[0,1] op_sel_hi:[1,0]
	v_mov_b32_e32 v33, v2
	v_mov_b32_e32 v35, v94
	v_mul_f32_e32 v2, v11, v11
	v_mul_f32_e32 v95, v4, v4
	v_pk_add_f32 v[32:33], v[32:33], v[34:35]
	v_pk_fma_f32 v[34:35], v[10:11], v[10:11], v[2:3] op_sel_hi:[1,1,0]
	v_mul_f32_e32 v2, v9, v9
	v_mul_f32_e32 v96, v5, v5
	v_mov_b32_e32 v35, v95
	v_pk_fma_f32 v[94:95], v[8:9], v[8:9], v[2:3] op_sel_hi:[1,1,0]
	s_nop 0
	v_mov_b32_e32 v95, v96
	v_pk_add_f32 v[34:35], v[34:35], v[94:95]
	v_lshlrev_b32_e32 v94, 16, v86
	v_pk_add_f32 v[32:33], v[32:33], v[34:35]
	v_and_b32_e32 v95, 0xffff0000, v86
	v_add_f32_e32 v2, v32, v33
	ds_bpermute_b32 v32, v89, v2
	v_mul_f32_e32 v86, 0xbfb8aa3b, v94
	v_exp_f32_e32 v86, v86
	s_waitcnt lgkmcnt(0)
	v_add_f32_e32 v2, v2, v32
	ds_bpermute_b32 v32, v90, v2
	v_add_f32_e32 v86, 1.0, v86
	v_rcp_f32_e32 v96, v86
	s_waitcnt lgkmcnt(0)
	v_add_f32_e32 v2, v2, v32
	v_fmamk_f32 v2, v2, 0x3c000000, v172
	v_cmp_gt_f32_e32 vcc, s33, v2
	v_mul_f32_e32 v32, 0x4b800000, v2
	s_nop 0
	v_cndmask_b32_e32 v2, v2, v32, vcc
	v_rsq_f32_e32 v2, v2
	s_nop 0
	v_mul_f32_e32 v32, 0x45800000, v2
	v_cndmask_b32_e32 v2, v2, v32, vcc
	v_pk_mul_f32 v[24:25], v[24:25], v[2:3] op_sel_hi:[1,0]
	v_pk_mul_f32 v[82:83], v[82:83], v[2:3] op_sel_hi:[1,0]
	v_pk_mul_f32 v[30:31], v[30:31], v[2:3] op_sel_hi:[1,0]
	v_pk_mul_f32 v[28:29], v[28:29], v[2:3] op_sel_hi:[1,0]
	v_pk_mul_f32 v[26:27], v[26:27], v[2:3] op_sel_hi:[1,0]
	v_pk_mul_f32 v[22:23], v[22:23], v[2:3] op_sel_hi:[1,0]
	v_pk_mul_f32 v[20:21], v[20:21], v[2:3] op_sel_hi:[1,0]
	v_pk_mul_f32 v[16:17], v[16:17], v[2:3] op_sel_hi:[1,0]
	v_pk_mul_f32 v[18:19], v[18:19], v[2:3] op_sel_hi:[1,0]
	v_pk_mul_f32 v[14:15], v[14:15], v[2:3] op_sel_hi:[1,0]
	v_pk_mul_f32 v[12:13], v[12:13], v[2:3] op_sel_hi:[1,0]
	v_pk_mul_f32 v[10:11], v[10:11], v[2:3] op_sel_hi:[1,0]
	v_pk_mul_f32 v[8:9], v[8:9], v[2:3] op_sel_hi:[1,0]
	v_pk_mul_f32 v[6:7], v[6:7], v[2:3] op_sel_hi:[1,0]
	v_pk_mul_f32 v[4:5], v[4:5], v[2:3] op_sel_hi:[1,0]
	s_andn2_b64 vcc, exec, s[6:7]
	s_mov_b64 s[6:7], 0
	s_waitcnt vmcnt(0)
	v_mov_b64_e32 v[32:33], v[184:185]
	v_mov_b64_e32 v[34:35], v[186:187]
	v_pk_mul_f32 v[24:25], v[32:33], v[24:25]
	v_mul_f32_e32 v32, 0xbfb8aa3b, v95
	v_exp_f32_e32 v32, v32
	s_nop 0
	v_add_f32_e32 v32, 1.0, v32
	v_rcp_f32_e32 v97, v32
	s_nop 0
	v_pk_mul_f32 v[32:33], v[96:97], v[94:95]
	s_nop 0
	v_pk_mul_f32 v[24:25], v[32:33], v[24:25]
	v_lshlrev_b32_e32 v32, 16, v87
	v_and_b32_e32 v33, 0xffff0000, v87
	v_mul_f32_e32 v86, 0xbfb8aa3b, v32
	v_mul_f32_e32 v87, 0xbfb8aa3b, v33
	v_exp_f32_e32 v86, v86
	v_exp_f32_e32 v87, v87
	v_pk_mul_f32 v[94:95], v[98:99], v[2:3] op_sel_hi:[1,0]
	v_add_f32_e32 v86, 1.0, v86
	v_add_f32_e32 v87, 1.0, v87
	v_rcp_f32_e32 v86, v86
	v_rcp_f32_e32 v87, v87
	v_pk_mul_f32 v[34:35], v[34:35], v[94:95]
	v_pk_mul_f32 v[32:33], v[86:87], v[32:33]
	s_nop 0
	v_pk_mul_f32 v[34:35], v[32:33], v[34:35]
	v_cvt_pk_bf16_f32 v32, v24, v25
	v_cvt_pk_bf16_f32 v33, v34, v35
	v_lshl_add_u64 v[24:25], v[66:67], 0, v[84:85]
	global_store_dwordx2 v[24:25], v[32:33], off
	v_lshlrev_b32_e32 v84, 16, v80
	v_and_b32_e32 v85, 0xffff0000, v80
	v_mul_f32_e32 v80, 0xbfb8aa3b, v84
	v_exp_f32_e32 v80, v80
	v_mov_b64_e32 v[32:33], v[188:189]
	v_mov_b64_e32 v[34:35], v[190:191]
	v_pk_mul_f32 v[32:33], v[32:33], v[82:83]
	v_add_f32_e32 v80, 1.0, v80
	v_rcp_f32_e32 v86, v80
	v_mul_f32_e32 v80, 0xbfb8aa3b, v85
	v_exp_f32_e32 v80, v80
	v_pk_mul_f32 v[30:31], v[34:35], v[30:31]
	v_add_f32_e32 v80, 1.0, v80
	v_rcp_f32_e32 v87, v80
	v_lshlrev_b32_e32 v80, 16, v81
	v_and_b32_e32 v81, 0xffff0000, v81
	v_mul_f32_e32 v34, 0xbfb8aa3b, v81
	v_pk_mul_f32 v[82:83], v[86:87], v[84:85]
	v_exp_f32_e32 v34, v34
	v_pk_mul_f32 v[32:33], v[82:83], v[32:33]
	v_mul_f32_e32 v82, 0xbfb8aa3b, v80
	v_exp_f32_e32 v82, v82
	v_add_f32_e32 v34, 1.0, v34
	v_rcp_f32_e32 v83, v34
	v_cvt_pk_bf16_f32 v32, v32, v33
	v_add_f32_e32 v82, 1.0, v82
	v_rcp_f32_e32 v82, v82
	s_nop 0
	v_pk_mul_f32 v[34:35], v[82:83], v[80:81]
	s_nop 0
	v_pk_mul_f32 v[30:31], v[34:35], v[30:31]
	v_lshlrev_b32_e32 v34, 16, v78
	v_cvt_pk_bf16_f32 v33, v30, v31
	global_store_dwordx2 v[24:25], v[32:33], off offset:32
	v_and_b32_e32 v35, 0xffff0000, v78
	v_mul_f32_e32 v78, 0xbfb8aa3b, v34
	v_exp_f32_e32 v78, v78
	v_mov_b64_e32 v[30:31], v[192:193]
	v_mov_b64_e32 v[32:33], v[194:195]
	v_pk_mul_f32 v[28:29], v[30:31], v[28:29]
	v_mul_f32_e32 v30, 0xbfb8aa3b, v35
	v_exp_f32_e32 v30, v30
	v_add_f32_e32 v78, 1.0, v78
	v_rcp_f32_e32 v80, v78
	v_pk_mul_f32 v[26:27], v[32:33], v[26:27]
	v_add_f32_e32 v30, 1.0, v30
	v_rcp_f32_e32 v81, v30
	s_nop 0
	v_pk_mul_f32 v[30:31], v[80:81], v[34:35]
	s_nop 0
	v_pk_mul_f32 v[28:29], v[30:31], v[28:29]
	v_lshlrev_b32_e32 v30, 16, v79
	v_and_b32_e32 v31, 0xffff0000, v79
	v_mul_f32_e32 v34, 0xbfb8aa3b, v30
	v_mul_f32_e32 v32, 0xbfb8aa3b, v31
	v_exp_f32_e32 v34, v34
	v_exp_f32_e32 v32, v32
	v_cvt_pk_bf16_f32 v28, v28, v29
	v_add_f32_e32 v34, 1.0, v34
	v_add_f32_e32 v32, 1.0, v32
	v_rcp_f32_e32 v34, v34
	v_rcp_f32_e32 v35, v32
	s_nop 0
	v_pk_mul_f32 v[30:31], v[34:35], v[30:31]
	s_nop 0
	v_pk_mul_f32 v[26:27], v[30:31], v[26:27]
	v_lshlrev_b32_e32 v30, 16, v76
	v_cvt_pk_bf16_f32 v29, v26, v27
	global_store_dwordx2 v[24:25], v[28:29], off offset:64
	v_and_b32_e32 v31, 0xffff0000, v76
	v_mul_f32_e32 v32, 0xbfb8aa3b, v30
	v_exp_f32_e32 v32, v32
	v_mov_b64_e32 v[26:27], v[196:197]
	v_mov_b64_e32 v[28:29], v[198:199]
	v_pk_mul_f32 v[22:23], v[26:27], v[22:23]
	v_mul_f32_e32 v26, 0xbfb8aa3b, v31
	v_exp_f32_e32 v26, v26
	v_add_f32_e32 v32, 1.0, v32
	v_rcp_f32_e32 v32, v32
	v_pk_mul_f32 v[20:21], v[28:29], v[20:21]
	v_add_f32_e32 v26, 1.0, v26
	v_rcp_f32_e32 v33, v26
	s_nop 0
	v_pk_mul_f32 v[26:27], v[32:33], v[30:31]
	s_nop 0
	v_pk_mul_f32 v[22:23], v[26:27], v[22:23]
	v_lshlrev_b32_e32 v26, 16, v77
	v_and_b32_e32 v27, 0xffff0000, v77
	v_mul_f32_e32 v30, 0xbfb8aa3b, v26
	v_mul_f32_e32 v28, 0xbfb8aa3b, v27
	v_exp_f32_e32 v30, v30
	v_exp_f32_e32 v28, v28
	v_cvt_pk_bf16_f32 v22, v22, v23
	v_add_f32_e32 v30, 1.0, v30
	v_add_f32_e32 v28, 1.0, v28
	v_rcp_f32_e32 v30, v30
	v_rcp_f32_e32 v31, v28
	s_nop 0
	v_pk_mul_f32 v[26:27], v[30:31], v[26:27]
	s_nop 0
	v_pk_mul_f32 v[20:21], v[26:27], v[20:21]
	v_lshlrev_b32_e32 v26, 16, v74
	v_cvt_pk_bf16_f32 v23, v20, v21
	global_store_dwordx2 v[24:25], v[22:23], off offset:96
	v_and_b32_e32 v27, 0xffff0000, v74
	v_mul_f32_e32 v28, 0xbfb8aa3b, v26
	v_exp_f32_e32 v28, v28
	v_mov_b64_e32 v[20:21], v[200:201]
	v_mov_b64_e32 v[22:23], v[202:203]
	v_pk_mul_f32 v[16:17], v[20:21], v[16:17]
	v_mul_f32_e32 v20, 0xbfb8aa3b, v27
	v_exp_f32_e32 v20, v20
	v_add_f32_e32 v28, 1.0, v28
	v_rcp_f32_e32 v28, v28
	v_pk_mul_f32 v[18:19], v[22:23], v[18:19]
	v_add_f32_e32 v20, 1.0, v20
	v_rcp_f32_e32 v29, v20
	s_nop 0
	v_pk_mul_f32 v[20:21], v[28:29], v[26:27]
	s_nop 0
	v_pk_mul_f32 v[16:17], v[20:21], v[16:17]
	v_lshlrev_b32_e32 v20, 16, v75
	v_and_b32_e32 v21, 0xffff0000, v75
	v_mul_f32_e32 v26, 0xbfb8aa3b, v20
	v_mul_f32_e32 v22, 0xbfb8aa3b, v21
	v_exp_f32_e32 v26, v26
	v_exp_f32_e32 v22, v22
	v_cvt_pk_bf16_f32 v16, v16, v17
	v_add_f32_e32 v26, 1.0, v26
	v_add_f32_e32 v22, 1.0, v22
	v_rcp_f32_e32 v26, v26
	v_rcp_f32_e32 v27, v22
	s_nop 0
	v_pk_mul_f32 v[20:21], v[26:27], v[20:21]
	s_nop 0
	v_pk_mul_f32 v[18:19], v[20:21], v[18:19]
	v_lshlrev_b32_e32 v20, 16, v72
	v_cvt_pk_bf16_f32 v17, v18, v19
	global_store_dwordx2 v[24:25], v[16:17], off offset:128
	v_and_b32_e32 v21, 0xffff0000, v72
	v_mul_f32_e32 v22, 0xbfb8aa3b, v20
	v_exp_f32_e32 v22, v22
	v_mov_b64_e32 v[16:17], v[204:205]
	v_mov_b64_e32 v[18:19], v[206:207]
	v_pk_mul_f32 v[14:15], v[16:17], v[14:15]
	v_mul_f32_e32 v16, 0xbfb8aa3b, v21
	v_exp_f32_e32 v16, v16
	v_add_f32_e32 v22, 1.0, v22
	v_rcp_f32_e32 v22, v22
	v_pk_mul_f32 v[12:13], v[18:19], v[12:13]
	v_add_f32_e32 v16, 1.0, v16
	v_rcp_f32_e32 v23, v16
	s_nop 0
	v_pk_mul_f32 v[16:17], v[22:23], v[20:21]
	s_nop 0
	v_pk_mul_f32 v[14:15], v[16:17], v[14:15]
	v_lshlrev_b32_e32 v16, 16, v73
	v_and_b32_e32 v17, 0xffff0000, v73
	v_mul_f32_e32 v20, 0xbfb8aa3b, v16
	v_mul_f32_e32 v18, 0xbfb8aa3b, v17
	v_exp_f32_e32 v20, v20
	v_exp_f32_e32 v18, v18
	v_cvt_pk_bf16_f32 v14, v14, v15
	v_add_f32_e32 v20, 1.0, v20
	v_add_f32_e32 v18, 1.0, v18
	v_rcp_f32_e32 v20, v20
	v_rcp_f32_e32 v21, v18
	s_nop 0
	v_pk_mul_f32 v[16:17], v[20:21], v[16:17]
	s_nop 0
	v_pk_mul_f32 v[12:13], v[16:17], v[12:13]
	v_lshlrev_b32_e32 v16, 16, v70
	v_cvt_pk_bf16_f32 v15, v12, v13
	global_store_dwordx2 v[24:25], v[14:15], off offset:160
	v_and_b32_e32 v17, 0xffff0000, v70
	v_mul_f32_e32 v18, 0xbfb8aa3b, v16
	v_exp_f32_e32 v18, v18
	v_mov_b64_e32 v[12:13], v[230:231]
	v_mov_b64_e32 v[14:15], v[232:233]
	v_pk_mul_f32 v[10:11], v[12:13], v[10:11]
	v_mul_f32_e32 v12, 0xbfb8aa3b, v17
	v_exp_f32_e32 v12, v12
	v_add_f32_e32 v18, 1.0, v18
	v_rcp_f32_e32 v18, v18
	v_pk_mul_f32 v[8:9], v[14:15], v[8:9]
	v_add_f32_e32 v12, 1.0, v12
	v_rcp_f32_e32 v19, v12
	s_nop 0
	v_pk_mul_f32 v[12:13], v[18:19], v[16:17]
	s_nop 0
	v_pk_mul_f32 v[10:11], v[12:13], v[10:11]
	v_lshlrev_b32_e32 v12, 16, v71
	v_and_b32_e32 v13, 0xffff0000, v71
	v_mul_f32_e32 v16, 0xbfb8aa3b, v12
	v_mul_f32_e32 v14, 0xbfb8aa3b, v13
	v_exp_f32_e32 v16, v16
	v_exp_f32_e32 v14, v14
	v_cvt_pk_bf16_f32 v10, v10, v11
	v_add_f32_e32 v16, 1.0, v16
	v_add_f32_e32 v14, 1.0, v14
	v_rcp_f32_e32 v16, v16
	v_rcp_f32_e32 v17, v14
	s_nop 0
	v_pk_mul_f32 v[12:13], v[16:17], v[12:13]
	s_nop 0
	v_pk_mul_f32 v[8:9], v[12:13], v[8:9]
	v_lshlrev_b32_e32 v12, 16, v68
	v_cvt_pk_bf16_f32 v11, v8, v9
	global_store_dwordx2 v[24:25], v[10:11], off offset:192
	v_and_b32_e32 v13, 0xffff0000, v68
	v_mul_f32_e32 v14, 0xbfb8aa3b, v12
	v_exp_f32_e32 v14, v14
	v_mov_b64_e32 v[8:9], v[234:235]
	v_mov_b64_e32 v[10:11], v[236:237]
	v_pk_mul_f32 v[6:7], v[6:7], v[8:9]
	v_mul_f32_e32 v8, 0xbfb8aa3b, v13
	v_exp_f32_e32 v8, v8
	v_add_f32_e32 v14, 1.0, v14
	v_rcp_f32_e32 v14, v14
	v_pk_mul_f32 v[4:5], v[4:5], v[10:11]
	v_add_f32_e32 v8, 1.0, v8
	v_rcp_f32_e32 v15, v8
	s_nop 0
	v_pk_mul_f32 v[8:9], v[14:15], v[12:13]
	s_nop 0
	v_pk_mul_f32 v[6:7], v[8:9], v[6:7]
	v_lshlrev_b32_e32 v8, 16, v69
	v_and_b32_e32 v9, 0xffff0000, v69
	v_mul_f32_e32 v12, 0xbfb8aa3b, v8
	v_mul_f32_e32 v2, 0xbfb8aa3b, v9
	v_exp_f32_e32 v12, v12
	v_exp_f32_e32 v2, v2
	v_cvt_pk_bf16_f32 v6, v6, v7
	v_add_f32_e32 v12, 1.0, v12
	v_add_f32_e32 v2, 1.0, v2
	v_rcp_f32_e32 v12, v12
	v_rcp_f32_e32 v13, v2
	s_nop 0
	v_pk_mul_f32 v[8:9], v[12:13], v[8:9]
	s_nop 0
	v_pk_mul_f32 v[4:5], v[8:9], v[4:5]
	s_nop 0
	v_cvt_pk_bf16_f32 v7, v4, v5
	global_store_dwordx2 v[24:25], v[6:7], off offset:224
	s_cbranch_vccz .LBB0_218
	v_readlane_b32 s6, v252, 7
	v_readlane_b32 s7, v252, 8
	s_load_dword s5, s[6:7], 0x0
	s_waitcnt lgkmcnt(0)
	s_add_i32 s4, s4, s5
	s_cmpk_gt_i32 s4, 0xff
	s_cbranch_scc0 .LBB0_217
